# diff loop fast path: straight-line QK block with V ks0 reads and DMA in MFMA gaps, trimmed header
# speedup vs baseline: 1.0154x; 1.0154x over previous
; #define LAS __attribute__((address_space(3)))
; #define MFMA32(a, b, c) __builtin_amdgcn_mfma_f32_32x32x16_bf16((a), (b), (c), 0, 0, 0)
; #define ATT_SB() __builtin_amdgcn_sched_barrier(0)
; template <bool FOX> ...
;     ...
;         const int tn = FOX ? t - 1 : t + 1, tn2 = FOX ? t - 2 : t + 2;
;         const bool have_next = FOX ? (tn >= 1) : (tn <= NT), have_next2 = FOX ? (tn2 >= 1) : (tn2 <= NT);
;         const int nbuf = (buf + 1) & 3;
;         const bool act = (t <= tq) && wmore;
;         LAS const unsigned char* vbp_ = lds + pbuf * 32768;
;         LAS const unsigned char* kb = lds + buf * 32768;
;         s16x4 va[NCB][2];
;         f32x16 s0, s1;
;         float ckfirst = 0.f, alpha_o = 1.f; bool resc = false;
;         if (act) {
;             bf16x8 kf[8];
; #pragma unroll
;             for (int s = 0; s < 4; ++s) { kf[2 * s] = *(LAS const bf16x8*)(kb + koff[s]); kf[2 * s + 1] = *(LAS const bf16x8*)(kb + koff[s] + 8192); }
;             if (have_next2) ATT_DMA(tn2, (buf + 2) & 3);
;             if (FOX) {
;                 LAS const float* ck = (LAS const float*)(lds + ATT_CK + buf * 512) + 64 * stream;
;                 ckfirst = ck[0] * LOG2E;
;                 ck += 8 * hi;
;                 const float cqm = cq2 - mref;
; #pragma unroll
;                 for (int rr = 0; rr < 2; ++rr) {
;                     const f32x4 a0 = *(LAS const f32x4*)(ck + 16 * rr), a1 = *(LAS const f32x4*)(ck + 16 * rr + 4), b0 = *(LAS const f32x4*)(ck + 32 + 16 * rr), b1 = *(LAS const f32x4*)(ck + 32 + 16 * rr + 4);
; #pragma unroll
;                     for (int e = 0; e < 4; ++e) { s0[8 * rr + e] = cqm - LOG2E * a0[e]; s0[8 * rr + 4 + e] = cqm - LOG2E * a1[e]; s1[8 * rr + e] = cqm - LOG2E * b0[e]; s1[8 * rr + 4 + e] = cqm - LOG2E * b1[e]; }
;                 }
;                 ATT_SB();
;                 s0 = MFMA32(kf[0], qf[0], s0); s1 = MFMA32(kf[1], qf[0], s1);
;             } else {
;                 ATT_SB();
;                 s0 = MFMA32(kf[0], qf[0], negm); s1 = MFMA32(kf[1], qf[0], negm);
;             }
; #pragma unroll
;             for (int s = 1; s < 4; ++s) { s0 = MFMA32(kf[2 * s], qf[s], s0); s1 = MFMA32(kf[2 * s + 1], qf[s], s1); }
;         } else {
;             if (have_next2) ATT_DMA(tn2, (buf + 2) & 3);
; #pragma unroll
;             for (int r = 0; r < 16; ++r) { s0[r] = -INFINITY; s1[r] = -INFINITY; }
;         }
;         ATT_VRD(va, 0);
.LBB0_562:
	s_add_i32 s14, s19, 0x82
	s_cmp_lt_u32 s14, s0
	s_cbranch_scc0 .Ldiff_slow
	s_cmp_le_u32 s14, s1
	s_cbranch_scc0 .Ldiff_slow
	s_cmp_eq_u64 s[8:9], 0
	s_cbranch_scc0 .Ldiff_slow
	s_mov_b32 s22, s6
	s_lshl_b32 s25, s22, 15
	s_lshl_b32 s29, s23, 15
	v_add_u32_e32 v17, s25, v238
	ds_read_b128 v[112:115], v17
	ds_read_b128 v[172:175], v17 offset:8192
	v_add_u32_e32 v17, s25, v239
	ds_read_b128 v[176:179], v17
	ds_read_b128 v[164:167], v17 offset:8192
	v_add_u32_e32 v17, s25, v240
	ds_read_b128 v[168:171], v17
	ds_read_b128 v[22:25], v17 offset:8192
	v_add_u32_e32 v17, s25, v241
	ds_read_b128 v[26:29], v17
	ds_read_b128 v[18:21], v17 offset:8192
	s_xor_b32 s15, s25, 0x10000
	s_lshl_b64 s[6:7], s[16:17], 10
	s_add_i32 s15, s24, s15
	s_add_i32 s25, s15, 0x400
	s_add_i32 s28, s15, 0x4000
	s_mov_b32 m0, s15
	v_lshl_add_u64 v[30:31], v[200:201], 0, s[6:7]
	s_waitcnt lgkmcnt(7)
	v_mfma_f32_32x32x16_bf16 v[128:143], v[112:115], v[2:5], v[96:111]
	global_load_lds_dwordx4 v[30:31], off
	s_mov_b32 m0, s25
	v_lshl_add_u64 v[30:31], v[198:199], 0, s[6:7]
	s_waitcnt lgkmcnt(5)
	v_mfma_f32_32x32x16_bf16 v[128:143], v[176:179], v[6:9], v[128:143]
	v_mfma_f32_32x32x16_bf16 v[112:127], v[172:175], v[2:5], v[96:111]
	global_load_lds_dwordx4 v[30:31], off
	s_mov_b32 m0, s28
	v_lshl_add_u64 v[30:31], v[196:197], 0, s[6:7]
	v_add_u32_e32 v172, s29, v209
	v_add_u32_e32 v173, s29, v237
	s_waitcnt lgkmcnt(3)
	v_mfma_f32_32x32x16_bf16 v[112:127], v[164:167], v[6:9], v[112:127]
	v_mfma_f32_32x32x16_bf16 v[128:143], v[168:171], v[10:13], v[128:143]
	global_load_lds_dwordx4 v[30:31], off
	v_lshl_add_u64 v[30:31], v[202:203], 0, s[6:7]
	s_add_i32 s6, s15, 0x4400
	s_mov_b32 m0, s6
	ds_read_b64_tr_b16 v[164:165], v172 offset:16384
	ds_read_b64_tr_b16 v[166:167], v173 offset:16384
	v_add_u32_e32 v168, s29, v205
	v_add_u32_e32 v169, s29, v206
	v_add_u32_e32 v170, s29, v207
	v_add_u32_e32 v171, s29, v208
	s_waitcnt lgkmcnt(3)
	v_mfma_f32_32x32x16_bf16 v[112:127], v[22:25], v[10:13], v[112:127]
	v_mfma_f32_32x32x16_bf16 v[128:143], v[26:29], v[144:147], v[128:143]
	global_load_lds_dwordx4 v[30:31], off
	ds_read_b64_tr_b16 v[22:23], v168 offset:16384
	ds_read_b64_tr_b16 v[24:25], v169 offset:16384
	ds_read_b64_tr_b16 v[26:27], v170 offset:16384
	ds_read_b64_tr_b16 v[28:29], v171 offset:16384
	s_waitcnt lgkmcnt(6)
	v_mfma_f32_32x32x16_bf16 v[112:127], v[18:21], v[144:147], v[112:127]
	v_add_u32_e32 v17, s29, v193
	v_add_u32_e32 v31, s29, v204
	ds_read_b64_tr_b16 v[18:19], v17 offset:16384
	ds_read_b64_tr_b16 v[20:21], v31 offset:16384
	s_mov_b64 s[6:7], 0
	s_mov_b64 s[10:11], 0
	s_branch .LBB0_578
